# runtime-gain transpose loops fully unrolled too: 32 weight + 32 gain loads in flight per item
# speedup vs baseline: 1.0046x; 1.0001x over previous
; __device__ __forceinline__ void transpose_item(const float* W, int K, int N, bf16_t* WT, const float* gain, int mode, LAS float* scr, int item, int lane) {
;     ...
; #pragma unroll 8
;     for (int i = 0; i < 32; ++i) { const int kk = 2 * i + (lane >> 5); float w = __builtin_nontemporal_load(W + (size_t)(k0 + kk) * N + n0 + (lane & 31)); if (gain) w *= gain[k0 + kk]; scr[kk * 33 + (lane & 31)] = w; }
.LBB0_326:
.LBB0_327:
	v_lshl_add_u64 v[164:165], v[6:7], 0, s[10:11]
	global_load_dword v100, v[164:165], off nt
	v_lshl_add_u64 v[166:167], v[18:19], 0, s[10:11]
	global_load_dword v101, v[166:167], off nt
	v_lshl_add_u64 v[168:169], v[16:17], 0, s[10:11]
	global_load_dword v102, v[168:169], off nt
	v_lshl_add_u64 v[170:171], v[14:15], 0, s[10:11]
	global_load_dword v103, v[170:171], off nt
	v_lshl_add_u64 v[172:173], v[12:13], 0, s[10:11]
	global_load_dword v104, v[172:173], off nt
	v_lshl_add_u64 v[174:175], v[8:9], 0, s[10:11]
	global_load_dword v105, v[174:175], off nt
	v_lshl_add_u64 v[176:177], v[4:5], 0, s[10:11]
	global_load_dword v106, v[176:177], off nt
	v_lshl_add_u64 v[178:179], v[2:3], 0, s[10:11]
	global_load_dword v107, v[178:179], off nt
	s_add_u32 s10, s10, 0x58000
	s_addc_u32 s11, s11, 0
	v_lshl_add_u64 v[164:165], v[6:7], 0, s[10:11]
	global_load_dword v108, v[164:165], off nt
	v_lshl_add_u64 v[166:167], v[18:19], 0, s[10:11]
	global_load_dword v109, v[166:167], off nt
	v_lshl_add_u64 v[168:169], v[16:17], 0, s[10:11]
	global_load_dword v110, v[168:169], off nt
	v_lshl_add_u64 v[170:171], v[14:15], 0, s[10:11]
	global_load_dword v111, v[170:171], off nt
	v_lshl_add_u64 v[172:173], v[12:13], 0, s[10:11]
	global_load_dword v112, v[172:173], off nt
	v_lshl_add_u64 v[174:175], v[8:9], 0, s[10:11]
	global_load_dword v113, v[174:175], off nt
	v_lshl_add_u64 v[176:177], v[4:5], 0, s[10:11]
	global_load_dword v114, v[176:177], off nt
	v_lshl_add_u64 v[178:179], v[2:3], 0, s[10:11]
	global_load_dword v115, v[178:179], off nt
	s_add_u32 s10, s10, 0x58000
	s_addc_u32 s11, s11, 0
	v_lshl_add_u64 v[164:165], v[6:7], 0, s[10:11]
	global_load_dword v116, v[164:165], off nt
	v_lshl_add_u64 v[166:167], v[18:19], 0, s[10:11]
	global_load_dword v117, v[166:167], off nt
	v_lshl_add_u64 v[168:169], v[16:17], 0, s[10:11]
	global_load_dword v118, v[168:169], off nt
	v_lshl_add_u64 v[170:171], v[14:15], 0, s[10:11]
	global_load_dword v119, v[170:171], off nt
	v_lshl_add_u64 v[172:173], v[12:13], 0, s[10:11]
	global_load_dword v120, v[172:173], off nt
	v_lshl_add_u64 v[174:175], v[8:9], 0, s[10:11]
	global_load_dword v121, v[174:175], off nt
	v_lshl_add_u64 v[176:177], v[4:5], 0, s[10:11]
	global_load_dword v122, v[176:177], off nt
	v_lshl_add_u64 v[178:179], v[2:3], 0, s[10:11]
	global_load_dword v123, v[178:179], off nt
	s_add_u32 s10, s10, 0x58000
	s_addc_u32 s11, s11, 0
	v_lshl_add_u64 v[164:165], v[6:7], 0, s[10:11]
	global_load_dword v124, v[164:165], off nt
	v_lshl_add_u64 v[166:167], v[18:19], 0, s[10:11]
	global_load_dword v125, v[166:167], off nt
	v_lshl_add_u64 v[168:169], v[16:17], 0, s[10:11]
	global_load_dword v126, v[168:169], off nt
	v_lshl_add_u64 v[170:171], v[14:15], 0, s[10:11]
	global_load_dword v127, v[170:171], off nt
	v_lshl_add_u64 v[172:173], v[12:13], 0, s[10:11]
	global_load_dword v128, v[172:173], off nt
	v_lshl_add_u64 v[174:175], v[8:9], 0, s[10:11]
	global_load_dword v129, v[174:175], off nt
	v_lshl_add_u64 v[176:177], v[4:5], 0, s[10:11]
	global_load_dword v130, v[176:177], off nt
	v_lshl_add_u64 v[178:179], v[2:3], 0, s[10:11]
	global_load_dword v131, v[178:179], off nt
	s_add_u32 s10, s10, 0x58000
	s_addc_u32 s11, s11, 0
	v_cndmask_b32_e64 v22, 0, 1, s[16:17]
	v_cmp_ne_u32_e64 s[40:41], 1, v22
	s_andn2_b64 vcc, exec, s[16:17]
	s_cbranch_vccnz .LBB0_329
	global_load_dword v132, v[10:11], off offset:-56
	global_load_dword v133, v[10:11], off offset:-48
	global_load_dword v134, v[10:11], off offset:-40
	global_load_dword v135, v[10:11], off offset:-32
	global_load_dword v136, v[10:11], off offset:-24
	global_load_dword v137, v[10:11], off offset:-16
	global_load_dword v138, v[10:11], off offset:-8
	global_load_dword v139, v[10:11], off
	global_load_dword v140, v[10:11], off offset:8
	global_load_dword v141, v[10:11], off offset:16
	global_load_dword v142, v[10:11], off offset:24
	global_load_dword v143, v[10:11], off offset:32
	global_load_dword v144, v[10:11], off offset:40
	global_load_dword v145, v[10:11], off offset:48
	global_load_dword v146, v[10:11], off offset:56
	global_load_dword v147, v[10:11], off offset:64
	global_load_dword v148, v[10:11], off offset:72
	global_load_dword v149, v[10:11], off offset:80
	global_load_dword v150, v[10:11], off offset:88
	global_load_dword v151, v[10:11], off offset:96
	global_load_dword v152, v[10:11], off offset:104
	global_load_dword v153, v[10:11], off offset:112
	global_load_dword v154, v[10:11], off offset:120
	global_load_dword v155, v[10:11], off offset:128
	global_load_dword v156, v[10:11], off offset:136
	global_load_dword v157, v[10:11], off offset:144
	global_load_dword v158, v[10:11], off offset:152
	global_load_dword v159, v[10:11], off offset:160
	global_load_dword v160, v[10:11], off offset:168
	global_load_dword v161, v[10:11], off offset:176
	global_load_dword v162, v[10:11], off offset:184
	global_load_dword v163, v[10:11], off offset:192
	s_waitcnt vmcnt(0)
	v_mul_f32_e32 v100, v100, v132
	v_mul_f32_e32 v101, v101, v133
	v_mul_f32_e32 v102, v102, v134
	v_mul_f32_e32 v103, v103, v135
	v_mul_f32_e32 v104, v104, v136
	v_mul_f32_e32 v105, v105, v137
	v_mul_f32_e32 v106, v106, v138
	v_mul_f32_e32 v107, v107, v139
	v_mul_f32_e32 v108, v108, v140
	v_mul_f32_e32 v109, v109, v141
	v_mul_f32_e32 v110, v110, v142
	v_mul_f32_e32 v111, v111, v143
	v_mul_f32_e32 v112, v112, v144
	v_mul_f32_e32 v113, v113, v145
	v_mul_f32_e32 v114, v114, v146
	v_mul_f32_e32 v115, v115, v147
	v_mul_f32_e32 v116, v116, v148
	v_mul_f32_e32 v117, v117, v149
	v_mul_f32_e32 v118, v118, v150
	v_mul_f32_e32 v119, v119, v151
	v_mul_f32_e32 v120, v120, v152
	v_mul_f32_e32 v121, v121, v153
	v_mul_f32_e32 v122, v122, v154
	v_mul_f32_e32 v123, v123, v155
	v_mul_f32_e32 v124, v124, v156
	v_mul_f32_e32 v125, v125, v157
	v_mul_f32_e32 v126, v126, v158
	v_mul_f32_e32 v127, v127, v159
	v_mul_f32_e32 v128, v128, v160
	v_mul_f32_e32 v129, v129, v161
	v_mul_f32_e32 v130, v130, v162
	v_mul_f32_e32 v131, v131, v163
; __device__ __forceinline__ void transpose_item(const float* W, int K, int N, bf16_t* WT, const float* gain, int mode, LAS float* scr, int item, int lane) {
;     ...
;     for (int i = 0; i < 32; ++i) { const int kk = 2 * i + (lane >> 5); float w = __builtin_nontemporal_load(W + (size_t)(k0 + kk) * N + n0 + (lane & 31)); if (gain) w *= gain[k0 + kk]; scr[kk * 33 + (lane & 31)] = w; }
.LBB0_329:
	s_waitcnt vmcnt(0)
	ds_write_b32 v20, v100
	ds_write_b32 v20, v101 offset:264
	ds_write_b32 v20, v102 offset:528
	ds_write_b32 v20, v103 offset:792
	ds_write_b32 v20, v104 offset:1056
	ds_write_b32 v20, v105 offset:1320
	ds_write_b32 v20, v106 offset:1584
	ds_write_b32 v20, v107 offset:1848
	ds_write_b32 v20, v108 offset:2112
	ds_write_b32 v20, v109 offset:2376
	ds_write_b32 v20, v110 offset:2640
	ds_write_b32 v20, v111 offset:2904
	ds_write_b32 v20, v112 offset:3168
	ds_write_b32 v20, v113 offset:3432
	ds_write_b32 v20, v114 offset:3696
	ds_write_b32 v20, v115 offset:3960
	ds_write_b32 v20, v116 offset:4224
	ds_write_b32 v20, v117 offset:4488
	ds_write_b32 v20, v118 offset:4752
	ds_write_b32 v20, v119 offset:5016
	ds_write_b32 v20, v120 offset:5280
	ds_write_b32 v20, v121 offset:5544
	ds_write_b32 v20, v122 offset:5808
	ds_write_b32 v20, v123 offset:6072
	ds_write_b32 v20, v124 offset:6336
	ds_write_b32 v20, v125 offset:6600
	ds_write_b32 v20, v126 offset:6864
	ds_write_b32 v20, v127 offset:7128
	ds_write_b32 v20, v128 offset:7392
	ds_write_b32 v20, v129 offset:7656
	ds_write_b32 v20, v130 offset:7920
	ds_write_b32 v20, v131 offset:8184
	v_add_u32_e32 v20, 0x2100, v20
	v_lshl_add_u64 v[10:11], v[10:11], 0, 64
	v_lshl_add_u64 v[10:11], v[10:11], 0, 64
	v_lshl_add_u64 v[10:11], v[10:11], 0, 64
	v_lshl_add_u64 v[10:11], v[10:11], 0, 64

; __device__ __forceinline__ void transpose_item(const float* W, int K, int N, bf16_t* WT, const float* gain, int mode, LAS float* scr, int item, int lane) {
;     ...
;     const int nblk = N / 32, kb = item / nblk, nb = item % nblk, k0 = 64 * kb, n0 = 32 * nb;
; #pragma unroll 8
;     for (int i = 0; i < 32; ++i) { const int kk = 2 * i + (lane >> 5); float w = __builtin_nontemporal_load(W + (size_t)(k0 + kk) * N + n0 + (lane & 31)); if (gain) w *= gain[k0 + kk]; scr[kk * 33 + (lane & 31)] = w; }
.LBB0_362:
.LBB0_363:
	v_cndmask_b32_e64 v0, 0, 1, s[18:19]
	v_cmp_ne_u32_e64 s[40:41], 1, v0
	global_load_dword v100, v[4:5], off nt
	v_add_u32_e32 v0, 0, v10
	v_add_u32_e32 v12, 2, v0
	v_mad_i64_i32 v[166:167], s[38:39], v12, s91, v[2:3]
	global_load_dword v101, v[166:167], off nt
	v_add_u32_e32 v12, 4, v0
	v_mad_i64_i32 v[168:169], s[38:39], v12, s91, v[2:3]
	global_load_dword v102, v[168:169], off nt
	v_add_u32_e32 v12, 6, v0
	v_mad_i64_i32 v[170:171], s[38:39], v12, s91, v[2:3]
	global_load_dword v103, v[170:171], off nt
	v_add_u32_e32 v12, 8, v0
	v_mad_i64_i32 v[172:173], s[38:39], v12, s91, v[2:3]
	global_load_dword v104, v[172:173], off nt
	v_add_u32_e32 v12, 10, v0
	v_mad_i64_i32 v[174:175], s[38:39], v12, s91, v[2:3]
	global_load_dword v105, v[174:175], off nt
	v_add_u32_e32 v12, 12, v0
	v_mad_i64_i32 v[176:177], s[38:39], v12, s91, v[2:3]
	global_load_dword v106, v[176:177], off nt
	v_add_u32_e32 v12, 14, v0
	v_mad_i64_i32 v[178:179], s[38:39], v12, s91, v[2:3]
	global_load_dword v107, v[178:179], off nt
	s_nop 4
	s_mov_b64 s[38:39], 0x24000
	v_lshl_add_u64 v[4:5], v[4:5], 0, s[38:39]
	global_load_dword v108, v[4:5], off nt
	v_add_u32_e32 v0, 16, v10
	v_add_u32_e32 v12, 2, v0
	v_mad_i64_i32 v[166:167], s[38:39], v12, s91, v[2:3]
	global_load_dword v109, v[166:167], off nt
	v_add_u32_e32 v12, 4, v0
	v_mad_i64_i32 v[168:169], s[38:39], v12, s91, v[2:3]
	global_load_dword v110, v[168:169], off nt
	v_add_u32_e32 v12, 6, v0
	v_mad_i64_i32 v[170:171], s[38:39], v12, s91, v[2:3]
	global_load_dword v111, v[170:171], off nt
	v_add_u32_e32 v12, 8, v0
	v_mad_i64_i32 v[172:173], s[38:39], v12, s91, v[2:3]
	global_load_dword v112, v[172:173], off nt
	v_add_u32_e32 v12, 10, v0
	v_mad_i64_i32 v[174:175], s[38:39], v12, s91, v[2:3]
	global_load_dword v113, v[174:175], off nt
	v_add_u32_e32 v12, 12, v0
	v_mad_i64_i32 v[176:177], s[38:39], v12, s91, v[2:3]
	global_load_dword v114, v[176:177], off nt
	v_add_u32_e32 v12, 14, v0
	v_mad_i64_i32 v[178:179], s[38:39], v12, s91, v[2:3]
	global_load_dword v115, v[178:179], off nt
	s_nop 4
	s_mov_b64 s[38:39], 0x24000
	v_lshl_add_u64 v[4:5], v[4:5], 0, s[38:39]
	global_load_dword v116, v[4:5], off nt
	v_add_u32_e32 v0, 32, v10
	v_add_u32_e32 v12, 2, v0
	v_mad_i64_i32 v[166:167], s[38:39], v12, s91, v[2:3]
	global_load_dword v117, v[166:167], off nt
	v_add_u32_e32 v12, 4, v0
	v_mad_i64_i32 v[168:169], s[38:39], v12, s91, v[2:3]
	global_load_dword v118, v[168:169], off nt
	v_add_u32_e32 v12, 6, v0
	v_mad_i64_i32 v[170:171], s[38:39], v12, s91, v[2:3]
	global_load_dword v119, v[170:171], off nt
	v_add_u32_e32 v12, 8, v0
	v_mad_i64_i32 v[172:173], s[38:39], v12, s91, v[2:3]
	global_load_dword v120, v[172:173], off nt
	v_add_u32_e32 v12, 10, v0
	v_mad_i64_i32 v[174:175], s[38:39], v12, s91, v[2:3]
	global_load_dword v121, v[174:175], off nt
	v_add_u32_e32 v12, 12, v0
	v_mad_i64_i32 v[176:177], s[38:39], v12, s91, v[2:3]
	global_load_dword v122, v[176:177], off nt
	v_add_u32_e32 v12, 14, v0
	v_mad_i64_i32 v[178:179], s[38:39], v12, s91, v[2:3]
	global_load_dword v123, v[178:179], off nt
	s_nop 4
	s_mov_b64 s[38:39], 0x24000
	v_lshl_add_u64 v[4:5], v[4:5], 0, s[38:39]
	global_load_dword v124, v[4:5], off nt
	v_add_u32_e32 v0, 48, v10
	v_add_u32_e32 v12, 2, v0
	v_mad_i64_i32 v[166:167], s[38:39], v12, s91, v[2:3]
	global_load_dword v125, v[166:167], off nt
	v_add_u32_e32 v12, 4, v0
	v_mad_i64_i32 v[168:169], s[38:39], v12, s91, v[2:3]
	global_load_dword v126, v[168:169], off nt
	v_add_u32_e32 v12, 6, v0
	v_mad_i64_i32 v[170:171], s[38:39], v12, s91, v[2:3]
	global_load_dword v127, v[170:171], off nt
	v_add_u32_e32 v12, 8, v0
	v_mad_i64_i32 v[172:173], s[38:39], v12, s91, v[2:3]
	global_load_dword v128, v[172:173], off nt
	v_add_u32_e32 v12, 10, v0
	v_mad_i64_i32 v[174:175], s[38:39], v12, s91, v[2:3]
	global_load_dword v129, v[174:175], off nt
	v_add_u32_e32 v12, 12, v0
	v_mad_i64_i32 v[176:177], s[38:39], v12, s91, v[2:3]
	global_load_dword v130, v[176:177], off nt
	v_add_u32_e32 v12, 14, v0
	v_mad_i64_i32 v[178:179], s[38:39], v12, s91, v[2:3]
	global_load_dword v131, v[178:179], off nt
	s_nop 4
	s_mov_b64 s[38:39], 0x24000
	v_lshl_add_u64 v[4:5], v[4:5], 0, s[38:39]
	s_andn2_b64 vcc, exec, s[18:19]
	s_cbranch_vccnz .LBB0_365
	global_load_dword v132, v[6:7], off offset:-56
	global_load_dword v133, v[6:7], off offset:-48
	global_load_dword v134, v[6:7], off offset:-40
	global_load_dword v135, v[6:7], off offset:-32
	global_load_dword v136, v[6:7], off offset:-24
	global_load_dword v137, v[6:7], off offset:-16
	global_load_dword v138, v[6:7], off offset:-8
	global_load_dword v139, v[6:7], off
	global_load_dword v140, v[6:7], off offset:8
	global_load_dword v141, v[6:7], off offset:16
	global_load_dword v142, v[6:7], off offset:24
	global_load_dword v143, v[6:7], off offset:32
	global_load_dword v144, v[6:7], off offset:40
	global_load_dword v145, v[6:7], off offset:48
	global_load_dword v146, v[6:7], off offset:56
	global_load_dword v147, v[6:7], off offset:64
	global_load_dword v148, v[6:7], off offset:72
	global_load_dword v149, v[6:7], off offset:80
	global_load_dword v150, v[6:7], off offset:88
	global_load_dword v151, v[6:7], off offset:96
	global_load_dword v152, v[6:7], off offset:104
	global_load_dword v153, v[6:7], off offset:112
	global_load_dword v154, v[6:7], off offset:120
	global_load_dword v155, v[6:7], off offset:128
	global_load_dword v156, v[6:7], off offset:136
	global_load_dword v157, v[6:7], off offset:144
	global_load_dword v158, v[6:7], off offset:152
	global_load_dword v159, v[6:7], off offset:160
	global_load_dword v160, v[6:7], off offset:168
	global_load_dword v161, v[6:7], off offset:176
	global_load_dword v162, v[6:7], off offset:184
	global_load_dword v163, v[6:7], off offset:192
	s_waitcnt vmcnt(0)
	v_mul_f32_e32 v100, v100, v132
	v_mul_f32_e32 v101, v101, v133
	v_mul_f32_e32 v102, v102, v134
	v_mul_f32_e32 v103, v103, v135
	v_mul_f32_e32 v104, v104, v136
	v_mul_f32_e32 v105, v105, v137
	v_mul_f32_e32 v106, v106, v138
	v_mul_f32_e32 v107, v107, v139
	v_mul_f32_e32 v108, v108, v140
	v_mul_f32_e32 v109, v109, v141
	v_mul_f32_e32 v110, v110, v142
	v_mul_f32_e32 v111, v111, v143
	v_mul_f32_e32 v112, v112, v144
	v_mul_f32_e32 v113, v113, v145
	v_mul_f32_e32 v114, v114, v146
	v_mul_f32_e32 v115, v115, v147
	v_mul_f32_e32 v116, v116, v148
	v_mul_f32_e32 v117, v117, v149
	v_mul_f32_e32 v118, v118, v150
	v_mul_f32_e32 v119, v119, v151
	v_mul_f32_e32 v120, v120, v152
	v_mul_f32_e32 v121, v121, v153
	v_mul_f32_e32 v122, v122, v154
	v_mul_f32_e32 v123, v123, v155
	v_mul_f32_e32 v124, v124, v156
	v_mul_f32_e32 v125, v125, v157
	v_mul_f32_e32 v126, v126, v158
	v_mul_f32_e32 v127, v127, v159
	v_mul_f32_e32 v128, v128, v160
	v_mul_f32_e32 v129, v129, v161
	v_mul_f32_e32 v130, v130, v162
	v_mul_f32_e32 v131, v131, v163
; __device__ __forceinline__ void transpose_item(const float* W, int K, int N, bf16_t* WT, const float* gain, int mode, LAS float* scr, int item, int lane) {
;     ...
;     for (int i = 0; i < 32; ++i) { const int kk = 2 * i + (lane >> 5); float w = __builtin_nontemporal_load(W + (size_t)(k0 + kk) * N + n0 + (lane & 31)); if (gain) w *= gain[k0 + kk]; scr[kk * 33 + (lane & 31)] = w; }
.LBB0_365:
	s_waitcnt vmcnt(0)
	ds_write_b32 v9, v100
	ds_write_b32 v9, v101 offset:264
	ds_write_b32 v9, v102 offset:528
	ds_write_b32 v9, v103 offset:792
	ds_write_b32 v9, v104 offset:1056
	ds_write_b32 v9, v105 offset:1320
	ds_write_b32 v9, v106 offset:1584
	ds_write_b32 v9, v107 offset:1848
	ds_write_b32 v9, v108 offset:2112
	ds_write_b32 v9, v109 offset:2376
	ds_write_b32 v9, v110 offset:2640
	ds_write_b32 v9, v111 offset:2904
	ds_write_b32 v9, v112 offset:3168
	ds_write_b32 v9, v113 offset:3432
	ds_write_b32 v9, v114 offset:3696
	ds_write_b32 v9, v115 offset:3960
	ds_write_b32 v9, v116 offset:4224
	ds_write_b32 v9, v117 offset:4488
	ds_write_b32 v9, v118 offset:4752
	ds_write_b32 v9, v119 offset:5016
	ds_write_b32 v9, v120 offset:5280
	ds_write_b32 v9, v121 offset:5544
	ds_write_b32 v9, v122 offset:5808
	ds_write_b32 v9, v123 offset:6072
	ds_write_b32 v9, v124 offset:6336
	ds_write_b32 v9, v125 offset:6600
	ds_write_b32 v9, v126 offset:6864
	ds_write_b32 v9, v127 offset:7128
	ds_write_b32 v9, v128 offset:7392
	ds_write_b32 v9, v129 offset:7656
	ds_write_b32 v9, v130 offset:7920
	ds_write_b32 v9, v131 offset:8184
	v_add_u32_e32 v9, 0x2100, v9
	v_lshl_add_u64 v[6:7], v[6:7], 0, 64
	v_lshl_add_u64 v[6:7], v[6:7], 0, 64
	v_lshl_add_u64 v[6:7], v[6:7], 0, 64
	v_lshl_add_u64 v[6:7], v[6:7], 0, 64
	s_mov_b32 s2, 64
	s_branch .LBB0_302
